# S12 with scalar-base + 32-bit VGPR offset form of the K/V LDS-DMA loads (drops eight 64-bit VALU address adds per iteration)
# speedup vs baseline: 1.0114x; 1.0097x over previous
; #define SBAR() __builtin_amdgcn_sched_barrier(0)
; __device__ __forceinline__ void finishSM(f32x16& p0, f32x16& p1, float alpha, float& l_reg, bf16x8& pa0, bf16x8& pa1, bf16x8& pa2, bf16x8& pa3) {
;   for (int r = 0; r < 16; ++r) p1[r] = __builtin_amdgcn_exp2f(p1[r]);
;   float ps = 0; for (int r = 0; r < 16; ++r) ps += p0[r]; for (int r = 0; r < 16; ++r) ps += p1[r];
;   { auto rr = __builtin_amdgcn_permlane32_swap(__float_as_uint(ps), __float_as_uint(ps), false, false);
;     ps = __uint_as_float(rr[0]) + __uint_as_float(rr[1]); }
;   l_reg = l_reg * alpha + ps;
;     ...
;   PK4(p0, 0, pa0); PK4(p0, 8, pa1); PK4(p1, 0, pa2); PK4(p1, 8, pa3);
;     ...
; }
; __device__ __forceinline__ void kload(bf16x8 (&kf)[8], const char* Ks, int r32, int hi, int sb) {
; #pragma unroll
;   for (int d0 = 0; d0 < 4; ++d0) { const int cb = sb + (d0 * 16 + hi * 8) * 2;
;     kf[2 * d0] = *reinterpret_cast<const bf16x8*>(Ks + KSWZ(r32, cb)); kf[2 * d0 + 1] = *reinterpret_cast<const bf16x8*>(Ks + KSWZ(32 + r32, cb)); }
; }
; __device__ __forceinline__ void kmma(f32x16& p0, f32x16& p1, const bf16x8 (&kf)[8], const bf16x8* qr) {
;   asm volatile("s_waitcnt lgkmcnt(0)" ::: "memory"); SBAR();
;   p0 = f32x16{}; p1 = f32x16{};
; #pragma unroll
;   for (int d0 = 0; d0 < 4; ++d0) { p0 = __builtin_amdgcn_mfma_f32_32x32x16_bf16(kf[2 * d0], qr[d0], p0, 0, 0, 0); p1 = __builtin_amdgcn_mfma_f32_32x32x16_bf16(kf[2 * d0 + 1], qr[d0], p1, 0, 0, 0); }
; }
.LBB0_770:
	ds_read_b128 v[82:85], v245
	ds_read_b128 v[86:89], v245 offset:8192
	ds_read_b128 v[130:133], v246
	ds_read_b128 v[134:137], v246 offset:8192
	ds_read_b128 v[206:209], v247
	ds_read_b128 v[210:213], v247 offset:8192
	ds_read_b128 v[214:217], v255
	ds_read_b128 v[218:221], v255 offset:8192
	v_exp_f32_e32 v148, v66
	v_add_f32_e32 v66, 0, v175
	v_add_f32_e32 v66, v177, v66
	v_add_f32_e32 v66, v192, v66
	v_add_f32_e32 v66, v195, v66
	v_add_f32_e32 v66, v196, v66
	v_add_f32_e32 v66, v199, v66
	v_add_f32_e32 v66, v200, v66
	v_add_f32_e32 v66, v203, v66
	v_add_f32_e32 v66, v176, v66
	v_add_f32_e32 v66, v193, v66
	v_add_f32_e32 v66, v194, v66
	v_add_f32_e32 v66, v197, v66
	v_add_f32_e32 v66, v198, v66
	v_exp_f32_e32 v149, v67
	v_add_f32_e32 v66, v201, v66
	s_waitcnt lgkmcnt(7)
	v_mfma_f32_32x32x16_bf16 v[98:113], v[82:85], v[126:129], 0
	v_exp_f32_e32 v150, v68
	s_and_b32 s13, s36, 0xc000
	v_add_f32_e32 v66, v202, v66
	v_add_u32_e32 v244, s13, v164
	v_exp_f32_e32 v151, v69
	ds_read_b64_tr_b16 v[228:229], v244 offset:0
	v_add_f32_e32 v66, v204, v66
	ds_read_b64_tr_b16 v[230:231], v244 offset:0x800
	ds_read_b64_tr_b16 v[232:233], v244 offset:0x1000
	ds_read_b64_tr_b16 v[234:235], v244 offset:0x1800
	s_waitcnt lgkmcnt(10)
	v_mfma_f32_32x32x16_bf16 v[82:97], v[86:89], v[126:129], 0
	v_exp_f32_e32 v186, v70
	ds_read_b64_tr_b16 v[236:237], v244 offset:0x2000
	v_add_f32_e32 v66, v148, v66
	ds_read_b64_tr_b16 v[238:239], v244 offset:0x2800
	v_exp_f32_e32 v187, v71
	ds_read_b64_tr_b16 v[240:241], v244 offset:0x3000
	v_add_f32_e32 v66, v149, v66
	ds_read_b64_tr_b16 v[242:243], v244 offset:0x3800
	v_exp_f32_e32 v188, v72
	s_add_i32 s37, s12, 2
	s_cmpk_lt_u32 s12, 0x7e
	s_cselect_b64 s[0:1], -1, 0
	s_waitcnt lgkmcnt(13)
	v_mfma_f32_32x32x16_bf16 v[98:113], v[130:133], v[122:125], v[98:113]
	v_add_f32_e32 v66, v150, v66
	s_and_b64 s[10:11], s[0:1], exec
	v_exp_f32_e32 v189, v73
	s_cselect_b32 s10, 0, 0xffffff80
	v_add_f32_e32 v66, v151, v66
	s_add_i32 s58, s37, s10
	v_exp_f32_e32 v205, v74
	s_and_b64 s[0:1], s[0:1], exec
	s_cselect_b32 s1, s9, s30
	s_cselect_b32 s0, s8, s26
	s_lshl_b64 s[10:11], s[58:59], 17
	s_waitcnt lgkmcnt(12)
	v_mfma_f32_32x32x16_bf16 v[82:97], v[134:137], v[122:125], v[82:97]
	v_add_f32_e32 v66, v186, v66
	s_lshl_b64 s[0:1], s[0:1], 11
	v_exp_f32_e32 v222, v75
	s_add_u32 s10, s10, s0
	v_add_f32_e32 v66, v187, v66
	s_addc_u32 s11, s11, s1
	v_exp_f32_e32 v223, v76
	s_add_u32 s0, s20, s10
	v_add_f32_e32 v66, v188, v66
	s_addc_u32 s1, s21, s11
	s_add_u32 s10, s22, s10
	s_addc_u32 s11, s23, s11
	s_waitcnt lgkmcnt(11)
	v_mfma_f32_32x32x16_bf16 v[98:113], v[206:209], v[118:121], v[98:113]
	v_exp_f32_e32 v224, v77
	s_and_b32 s13, s37, 0xff
	v_add_f32_e32 v66, v189, v66
	s_mulk_i32 s13, 0xab
	v_exp_f32_e32 v225, v78
	s_lshr_b32 s13, s13, 9
	v_add_f32_e32 v66, v205, v66
	s_mul_i32 s13, s13, 3
	s_sub_i32 s13, s37, s13
	s_and_b32 s13, s13, 0xff
	s_waitcnt lgkmcnt(10)
	v_mfma_f32_32x32x16_bf16 v[82:97], v[210:213], v[118:121], v[82:97]
	v_exp_f32_e32 v226, v79
	s_lshl_b32 s13, s13, 14
	s_mov_b32 s100, s13
	v_add_f32_e32 v66, v222, v66
	s_add_i32 s42, s36, 0xffffc000
	v_exp_f32_e32 v227, v80
	s_and_b32 s42, s42, 0xc000
	v_add_f32_e32 v66, v223, v66
	s_add_i32 s13, s13, s27
	v_exp_f32_e32 v81, v81
	s_add_i32 s42, s42, s31
	s_mov_b32 m0, s13
	s_waitcnt lgkmcnt(9)
	v_mfma_f32_32x32x16_bf16 v[98:113], v[214:217], v[114:117], v[98:113]
	v_add_f32_e32 v66, v224, v66
	v_add_f32_e32 v66, v225, v66
	global_load_lds_dwordx4 v146, s[0:1]
	v_add_f32_e32 v66, v226, v66
	v_add_f32_e32 v66, v227, v66
	s_mov_b32 m0, s42
	s_nop 0
	global_load_lds_dwordx4 v142, s[10:11]
	s_waitcnt lgkmcnt(8)
	v_mfma_f32_32x32x16_bf16 v[82:97], v[218:221], v[114:117], v[82:97]
	v_add_f32_e32 v130, v81, v66
	s_add_i32 m0, s13, 0x2000
	v_mov_b32_e32 v131, v130
	v_cvt_pk_bf16_f32 v66, v175, v177
	global_load_lds_dwordx4 v144, s[0:1]
	v_cvt_pk_bf16_f32 v67, v192, v195
	v_cvt_pk_bf16_f32 v68, v196, v199
	s_add_i32 m0, s42, 0x2000
	s_nop 0
	global_load_lds_dwordx4 v154, s[10:11]
	v_permlane32_swap_b32_e32 v130, v131
	v_cvt_pk_bf16_f32 v69, v200, v203
	v_permlane32_swap_b32_e32 v66, v68
	v_cvt_pk_bf16_f32 v70, v176, v193
	v_cvt_pk_bf16_f32 v71, v194, v197
	v_cvt_pk_bf16_f32 v72, v198, v201
	v_cvt_pk_bf16_f32 v73, v202, v204
	v_cvt_pk_bf16_f32 v74, v148, v149
	v_cvt_pk_bf16_f32 v75, v150, v151
	v_cvt_pk_bf16_f32 v76, v186, v187
	v_cvt_pk_bf16_f32 v77, v188, v189
	v_cvt_pk_bf16_f32 v78, v205, v222
	v_cvt_pk_bf16_f32 v79, v223, v224
	v_cvt_pk_bf16_f32 v80, v225, v226
	v_cvt_pk_bf16_f32 v81, v227, v81
	v_permlane32_swap_b32_e32 v67, v69
	v_permlane32_swap_b32_e32 v70, v72
	v_permlane32_swap_b32_e32 v71, v73
	v_permlane32_swap_b32_e32 v74, v76
	v_permlane32_swap_b32_e32 v75, v77
	v_permlane32_swap_b32_e32 v78, v80
	v_permlane32_swap_b32_e32 v79, v81
	ds_read_b64_tr_b16 v[204:205], v244 offset:0x200
	ds_read_b64_tr_b16 v[206:207], v244 offset:0xa00
	ds_read_b64_tr_b16 v[208:209], v244 offset:0x1200
	ds_read_b64_tr_b16 v[210:211], v244 offset:0x1a00
	ds_read_b64_tr_b16 v[212:213], v244 offset:0x2200
	ds_read_b64_tr_b16 v[214:215], v244 offset:0x2a00
	ds_read_b64_tr_b16 v[216:217], v244 offset:0x3200
	ds_read_b64_tr_b16 v[218:219], v244 offset:0x3a00
	s_waitcnt lgkmcnt(14)
	v_mfma_f32_32x32x16_bf16 v[18:33], v[66:69], v[228:231], v[18:33]
	v_max_f32_e32 v245, v99, v99
	v_max_f32_e32 v246, v98, v98
	v_max_f32_e32 v245, v246, v245
	v_max3_f32 v245, v245, v100, v101
	v_max3_f32 v245, v245, v102, v103
	v_max3_f32 v245, v245, v104, v105
	v_max3_f32 v245, v245, v106, v107
	v_max3_f32 v245, v245, v108, v109
	s_waitcnt lgkmcnt(12)
; __device__ __forceinline__ void partialSM(f32x16& p0, f32x16& p1, float& m_reg, float& mn, float& alpha) {
;   constexpr float C = SCALE * 1.4426950408889634f;
;   float pmax = p0[0]; for (int r = 1; r < 16; ++r) pmax = fmaxf(pmax, p0[r]); for (int r = 0; r < 16; ++r) pmax = fmaxf(pmax, p1[r]);
;   { auto rr = __builtin_amdgcn_permlane32_swap(__float_as_uint(pmax), __float_as_uint(pmax), false, false);
;     pmax = fmaxf(__uint_as_float(rr[0]), __uint_as_float(rr[1])); }
;   if (__builtin_expect(__all(pmax - m_reg <= THR / SCALE), 1)) { mn = m_reg; alpha = 1.f; }
;   else { mn = fmaxf(m_reg, pmax); alpha = __builtin_amdgcn_exp2f((m_reg - mn) * C); m_reg = mn; }
;   float mnC = -mn * C;
;   for (int r = 0; r < 16; ++r) p0[r] = fmaf(p0[r], C, mnC); for (int r = 0; r < 16; ++r) p1[r] = fmaf(p1[r], C, mnC);
;   for (int r = 0; r < 16; ++r) p0[r] = __builtin_amdgcn_exp2f(p0[r]);
; }
; __device__ __forceinline__ void pv_mma(f32x16& od, const VFrag& f, bf16x8 pa0, bf16x8 pa1, bf16x8 pa2, bf16x8 pa3) {
;     ...
;   od = __builtin_amdgcn_mfma_f32_32x32x16_bf16(pa0, PK(f.l0, f.h0), od, 0, 0, 0);
;   od = __builtin_amdgcn_mfma_f32_32x32x16_bf16(pa1, PK(f.l1, f.h1), od, 0, 0, 0);
;   od = __builtin_amdgcn_mfma_f32_32x32x16_bf16(pa2, PK(f.l2, f.h2), od, 0, 0, 0);
;   od = __builtin_amdgcn_mfma_f32_32x32x16_bf16(pa3, PK(f.l3, f.h3), od, 0, 0, 0);
;     ...
; }
; __device__ __forceinline__ void pv_d0(f32x16* o, int vb, bf16x8 pa0, bf16x8 pa1, bf16x8 pa2, bf16x8 pa3) {
;   VFrag fa, fb;
;   v_frag_read<0>(fa, vb);
;   asm volatile("s_waitcnt lgkmcnt(0)" ::: "memory"); SBAR();
;   v_frag_read<1>(fb, vb); SBAR();
;   pv_mma(o[0], fa, pa0, pa1, pa2, pa3); SBAR();
;   asm volatile("s_waitcnt lgkmcnt(0)" ::: "memory"); SBAR();
;   v_frag_read<2>(fa, vb); SBAR();
;   pv_mma(o[1], fb, pa0, pa1, pa2, pa3); SBAR();
;   asm volatile("s_waitcnt lgkmcnt(0)" ::: "memory"); SBAR();
;   v_frag_read<3>(fb, vb); SBAR();
;   pv_mma(o[2], fa, pa0, pa1, pa2, pa3); SBAR();
;   asm volatile("s_waitcnt lgkmcnt(0)" ::: "memory"); SBAR();
;   pv_mma(o[3], fb, pa0, pa1, pa2, pa3);
; }
; __device__ __forceinline__ void attn_unit(const bf16* __restrict__ Qb, const bf16* __restrict__ Kh, const bf16* __restrict__ Vh, int klat0, int nlt, int kctx0, int NT,
;                                           float lam, float post, const float* __restrict__ subw, bf16* __restrict__ Ob, char* lds) {
	v_mfma_f32_32x32x16_bf16 v[18:33], v[70:73], v[232:235], v[18:33]
	v_max3_f32 v245, v245, v110, v111
	v_max3_f32 v245, v245, v112, v113
	v_max3_f32 v245, v245, v82, v83
	v_max3_f32 v245, v245, v84, v85
	v_max3_f32 v245, v245, v86, v87
	v_max3_f32 v245, v245, v88, v89
	v_max3_f32 v245, v245, v90, v91
	v_max3_f32 v245, v245, v92, v93
	s_waitcnt lgkmcnt(10)
	v_mfma_f32_32x32x16_bf16 v[18:33], v[74:77], v[236:239], v[18:33]
	v_max3_f32 v245, v245, v94, v95
	v_max3_f32 v245, v245, v96, v97
	v_mov_b32_e32 v246, v245
	s_nop 1
	v_permlane32_swap_b32_e32 v245, v246
	v_max_f32_e32 v246, v246, v246
	v_max_f32_e32 v245, v245, v245
	v_max_f32_e32 v245, v245, v246
	v_sub_f32_e32 v246, v245, v174
	s_waitcnt lgkmcnt(8)
	v_mfma_f32_32x32x16_bf16 v[18:33], v[78:81], v[240:243], v[18:33]
	v_cmp_ge_f32_e32 vcc, s63, v246
	v_max_f32_e32 v246, v174, v174
	v_max_f32_e32 v245, v246, v245
	v_sub_f32_e32 v246, v174, v245
	v_mul_f32_e32 v246, 0x3e38aa3b, v246
	v_exp_f32_e32 v246, v246
	s_cmp_eq_u64 vcc, exec
	s_cselect_b64 s[0:1], -1, 0
	v_cndmask_b32_e64 v132, v246, 1.0, s[0:1]
	ds_read_b64_tr_b16 v[228:229], v244 offset:0x400
	ds_read_b64_tr_b16 v[230:231], v244 offset:0xc00
	ds_read_b64_tr_b16 v[232:233], v244 offset:0x1400
	ds_read_b64_tr_b16 v[234:235], v244 offset:0x1c00
	ds_read_b64_tr_b16 v[236:237], v244 offset:0x2400
	ds_read_b64_tr_b16 v[238:239], v244 offset:0x2c00
	ds_read_b64_tr_b16 v[240:241], v244 offset:0x3400
	ds_read_b64_tr_b16 v[242:243], v244 offset:0x3c00
	v_cndmask_b32_e64 v133, v245, v174, s[0:1]
	v_mul_f32_e32 v148, 0xbe38aa3b, v133
	s_waitcnt lgkmcnt(14)
	v_mfma_f32_32x32x16_bf16 v[50:65], v[66:69], v[204:207], v[50:65]
	v_fmamk_f32 v98, v98, 0x3e38aa3b, v148
	v_fmamk_f32 v99, v99, 0x3e38aa3b, v148
	v_fmamk_f32 v100, v100, 0x3e38aa3b, v148
	v_fmamk_f32 v101, v101, 0x3e38aa3b, v148
	s_waitcnt lgkmcnt(12)
	v_mfma_f32_32x32x16_bf16 v[50:65], v[70:73], v[208:211], v[50:65]
	v_fmamk_f32 v102, v102, 0x3e38aa3b, v148
	v_fmamk_f32 v103, v103, 0x3e38aa3b, v148
	v_fmamk_f32 v104, v104, 0x3e38aa3b, v148
	v_fmamk_f32 v105, v105, 0x3e38aa3b, v148
	s_waitcnt lgkmcnt(10)
	v_mfma_f32_32x32x16_bf16 v[50:65], v[74:77], v[212:215], v[50:65]
	v_fmamk_f32 v106, v106, 0x3e38aa3b, v148
	v_fmamk_f32 v107, v107, 0x3e38aa3b, v148
	v_fmamk_f32 v108, v108, 0x3e38aa3b, v148
	v_fmamk_f32 v109, v109, 0x3e38aa3b, v148
	s_waitcnt lgkmcnt(8)
	v_mfma_f32_32x32x16_bf16 v[50:65], v[78:81], v[216:219], v[50:65]
	v_fmamk_f32 v110, v110, 0x3e38aa3b, v148
	v_fmamk_f32 v111, v111, 0x3e38aa3b, v148
	v_fmamk_f32 v112, v112, 0x3e38aa3b, v148
	v_fmamk_f32 v113, v113, 0x3e38aa3b, v148
	ds_read_b64_tr_b16 v[204:205], v244 offset:0x600
	ds_read_b64_tr_b16 v[206:207], v244 offset:0xe00
	ds_read_b64_tr_b16 v[208:209], v244 offset:0x1600
	ds_read_b64_tr_b16 v[210:211], v244 offset:0x1e00
	ds_read_b64_tr_b16 v[212:213], v244 offset:0x2600
	ds_read_b64_tr_b16 v[214:215], v244 offset:0x2e00
	ds_read_b64_tr_b16 v[216:217], v244 offset:0x3600
	ds_read_b64_tr_b16 v[218:219], v244 offset:0x3e00
	s_waitcnt lgkmcnt(14)
	v_mfma_f32_32x32x16_bf16 v[34:49], v[66:69], v[228:231], v[34:49]
	v_fmamk_f32 v82, v82, 0x3e38aa3b, v148
	v_fmamk_f32 v83, v83, 0x3e38aa3b, v148
	v_fmamk_f32 v84, v84, 0x3e38aa3b, v148
	v_fmamk_f32 v85, v85, 0x3e38aa3b, v148
	s_waitcnt lgkmcnt(12)
	v_mfma_f32_32x32x16_bf16 v[34:49], v[70:73], v[232:235], v[34:49]
	v_fmamk_f32 v86, v86, 0x3e38aa3b, v148
	v_fmamk_f32 v87, v87, 0x3e38aa3b, v148
	s_add_i32 s13, s36, 0xffff4000
	v_fmamk_f32 v149, v88, 0x3e38aa3b, v148
	s_waitcnt lgkmcnt(10)
	v_mfma_f32_32x32x16_bf16 v[34:49], v[74:77], v[236:239], v[34:49]
	v_fmamk_f32 v150, v89, 0x3e38aa3b, v148
	v_fmamk_f32 v151, v90, 0x3e38aa3b, v148
	v_fmamk_f32 v186, v91, 0x3e38aa3b, v148
	v_fmamk_f32 v187, v92, 0x3e38aa3b, v148
	s_waitcnt lgkmcnt(8)
	v_mfma_f32_32x32x16_bf16 v[34:49], v[78:81], v[240:243], v[34:49]
	v_fmamk_f32 v188, v93, 0x3e38aa3b, v148
	v_fmamk_f32 v189, v94, 0x3e38aa3b, v148
	v_exp_f32_e32 v192, v98
	v_exp_f32_e32 v193, v99
	v_exp_f32_e32 v194, v100
	v_exp_f32_e32 v195, v101
	s_waitcnt lgkmcnt(6)
	v_mfma_f32_32x32x16_bf16 v[2:17], v[66:69], v[204:207], v[2:17]
	v_exp_f32_e32 v196, v102
	v_exp_f32_e32 v197, v103
	v_exp_f32_e32 v198, v104
	v_exp_f32_e32 v199, v105
	s_waitcnt lgkmcnt(4)
	v_mfma_f32_32x32x16_bf16 v[2:17], v[70:73], v[208:211], v[2:17]
	v_exp_f32_e32 v200, v106
	v_exp_f32_e32 v201, v107
	v_exp_f32_e32 v202, v108
	v_exp_f32_e32 v203, v109
	v_exp_f32_e32 v204, v110
	v_exp_f32_e32 v205, v111
	s_waitcnt lgkmcnt(2)
	v_mfma_f32_32x32x16_bf16 v[2:17], v[74:77], v[212:215], v[2:17]
	v_exp_f32_e32 v206, v112
	v_exp_f32_e32 v207, v113
	v_fmamk_f32 v208, v95, 0x3e38aa3b, v148
	v_fmamk_f32 v209, v96, 0x3e38aa3b, v148
	v_fmac_f32_e32 v148, 0x3e38aa3b, v97
	s_waitcnt lgkmcnt(0)
	v_mfma_f32_32x32x16_bf16 v[2:17], v[78:81], v[216:219], v[2:17]
	v_add_u32_e32 v245, s101, v169
	v_add_u32_e32 v246, s101, v170
	v_add_u32_e32 v247, s101, v171
	v_add_u32_e32 v255, s101, v172
	v_cmp_gt_f32_e32 vcc, 1.0, v132
	s_cbranch_vccz .LBB0_774
	s_and_saveexec_b64 s[10:11], s[40:41]
	ds_write_b32 v162, v132 offset:128
	s_or_b64 exec, exec, s[10:11]
	s_waitcnt lgkmcnt(0)
	v_add_u32_e32 v67, s18, v140
	ds_read_b128 v[68:71], v67 offset:224
	ds_read_b128 v[72:75], v67 offset:192
	ds_read_b128 v[76:79], v67 offset:160
	ds_read_b128 v[134:137], v67 offset:128
	s_waitcnt lgkmcnt(0)
	v_pk_mul_f32 v[30:31], v[30:31], v[68:69]
	v_pk_mul_f32 v[26:27], v[26:27], v[72:73]
	v_pk_mul_f32 v[22:23], v[22:23], v[76:77]
	v_pk_mul_f32 v[32:33], v[32:33], v[70:71]
	v_pk_mul_f32 v[28:29], v[28:29], v[74:75]
	v_pk_mul_f32 v[24:25], v[24:25], v[78:79]
	v_pk_mul_f32 v[20:21], v[20:21], v[136:137]
	v_pk_mul_f32 v[18:19], v[18:19], v[134:135]
	v_pk_mul_f32 v[62:63], v[62:63], v[68:69]
	v_pk_mul_f32 v[58:59], v[58:59], v[72:73]
	v_pk_mul_f32 v[54:55], v[54:55], v[76:77]
	v_pk_mul_f32 v[64:65], v[64:65], v[70:71]
	v_pk_mul_f32 v[60:61], v[60:61], v[74:75]
	v_pk_mul_f32 v[56:57], v[56:57], v[78:79]
	v_pk_mul_f32 v[52:53], v[52:53], v[136:137]
	v_pk_mul_f32 v[50:51], v[50:51], v[134:135]
	v_pk_mul_f32 v[46:47], v[46:47], v[68:69]
	v_pk_mul_f32 v[42:43], v[42:43], v[72:73]
	v_pk_mul_f32 v[38:39], v[38:39], v[76:77]
	v_pk_mul_f32 v[48:49], v[48:49], v[70:71]
	v_pk_mul_f32 v[44:45], v[44:45], v[74:75]
	v_pk_mul_f32 v[40:41], v[40:41], v[78:79]
	v_pk_mul_f32 v[36:37], v[36:37], v[136:137]
	v_pk_mul_f32 v[34:35], v[34:35], v[134:135]
	v_pk_mul_f32 v[14:15], v[14:15], v[68:69]
	v_pk_mul_f32 v[10:11], v[10:11], v[72:73]
	v_pk_mul_f32 v[6:7], v[6:7], v[76:77]
	v_pk_mul_f32 v[16:17], v[16:17], v[70:71]
	v_pk_mul_f32 v[12:13], v[12:13], v[74:75]
	v_pk_mul_f32 v[8:9], v[8:9], v[78:79]
	v_pk_mul_f32 v[4:5], v[4:5], v[136:137]
	v_pk_mul_f32 v[2:3], v[2:3], v[134:135]
; #define SBAR() __builtin_amdgcn_sched_barrier(0)
; __device__ __forceinline__ void finishSM(f32x16& p0, f32x16& p1, float alpha, float& l_reg, bf16x8& pa0, bf16x8& pa1, bf16x8& pa2, bf16x8& pa3) {
;   for (int r = 0; r < 16; ++r) p1[r] = __builtin_amdgcn_exp2f(p1[r]);
;   float ps = 0; for (int r = 0; r < 16; ++r) ps += p0[r]; for (int r = 0; r < 16; ++r) ps += p1[r];
;   { auto rr = __builtin_amdgcn_permlane32_swap(__float_as_uint(ps), __float_as_uint(ps), false, false);
;     ps = __uint_as_float(rr[0]) + __uint_as_float(rr[1]); }
;   l_reg = l_reg * alpha + ps;
;     ...
;   PK4(p0, 0, pa0); PK4(p0, 8, pa1); PK4(p1, 0, pa2); PK4(p1, 8, pa3);
;     ...
; }
; __device__ __forceinline__ void kload(bf16x8 (&kf)[8], const char* Ks, int r32, int hi, int sb) {
; #pragma unroll
;   for (int d0 = 0; d0 < 4; ++d0) { const int cb = sb + (d0 * 16 + hi * 8) * 2;
;     kf[2 * d0] = *reinterpret_cast<const bf16x8*>(Ks + KSWZ(r32, cb)); kf[2 * d0 + 1] = *reinterpret_cast<const bf16x8*>(Ks + KSWZ(32 + r32, cb)); }
; }
; __device__ __forceinline__ void kmma(f32x16& p0, f32x16& p1, const bf16x8 (&kf)[8], const bf16x8* qr) {
;   asm volatile("s_waitcnt lgkmcnt(0)" ::: "memory"); SBAR();
;   p0 = f32x16{}; p1 = f32x16{};
; #pragma unroll
;   for (int d0 = 0; d0 < 4; ++d0) { p0 = __builtin_amdgcn_mfma_f32_32x32x16_bf16(kf[2 * d0], qr[d0], p0, 0, 0, 0); p1 = __builtin_amdgcn_mfma_f32_32x32x16_bf16(kf[2 * d0 + 1], qr[d0], p1, 0, 0, 0); }
; }
; __device__ __forceinline__ void qkt(f32x16& p0, f32x16& p1, const char* Ks, const bf16x8* qr, int r32, int hi, int sb) {
;   bf16x8 kf[8]; kload(kf, Ks, r32, hi, sb); SBAR(); kmma(p0, p1, kf, qr);
.LBB0_774:
	s_waitcnt vmcnt(4)
	s_barrier
	ds_read_b128 v[66:69], v245
	ds_read_b128 v[70:73], v245 offset:8192
	ds_read_b128 v[98:101], v246
	ds_read_b128 v[102:105], v246 offset:8192
	ds_read_b128 v[106:109], v247
	ds_read_b128 v[110:113], v247 offset:8192
	ds_read_b128 v[134:137], v255
	ds_read_b128 v[174:177], v255 offset:8192
	v_exp_f32_e32 v210, v82
	v_exp_f32_e32 v211, v83
	v_exp_f32_e32 v212, v84
	v_exp_f32_e32 v213, v85
	v_exp_f32_e32 v214, v86
	v_exp_f32_e32 v215, v87
	v_add_f32_e32 v216, 0, v192
	v_add_f32_e32 v216, v193, v216
	v_add_f32_e32 v216, v194, v216
	v_add_f32_e32 v216, v195, v216
	v_exp_f32_e32 v149, v149
	v_exp_f32_e32 v150, v150
	v_exp_f32_e32 v151, v151
	v_exp_f32_e32 v186, v186
	v_exp_f32_e32 v187, v187
	v_exp_f32_e32 v188, v188
	s_waitcnt lgkmcnt(7)
	v_mfma_f32_32x32x16_bf16 v[82:97], v[66:69], v[126:129], 0
	v_exp_f32_e32 v189, v189
	s_and_b32 s46, s13, 0xc000
	v_exp_f32_e32 v208, v208
	v_add_u32_e32 v244, s46, v164
	v_exp_f32_e32 v209, v209
	ds_read_b64_tr_b16 v[228:229], v244 offset:0
	v_exp_f32_e32 v148, v148
	ds_read_b64_tr_b16 v[230:231], v244 offset:0x800
	ds_read_b64_tr_b16 v[232:233], v244 offset:0x1000
	s_waitcnt lgkmcnt(9)
	v_mfma_f32_32x32x16_bf16 v[66:81], v[70:73], v[126:129], 0
	v_add_f32_e32 v255, v196, v216
	ds_read_b64_tr_b16 v[234:235], v244 offset:0x1800
	v_add_f32_e32 v255, v197, v255
	ds_read_b64_tr_b16 v[236:237], v244 offset:0x2000
	v_add_f32_e32 v255, v198, v255
	ds_read_b64_tr_b16 v[238:239], v244 offset:0x2800
	v_add_f32_e32 v255, v199, v255
	ds_read_b64_tr_b16 v[240:241], v244 offset:0x3000
	v_add_f32_e32 v255, v200, v255
	ds_read_b64_tr_b16 v[242:243], v244 offset:0x3800
	s_waitcnt lgkmcnt(13)
	v_mfma_f32_32x32x16_bf16 v[82:97], v[98:101], v[122:125], v[82:97]
	v_add_f32_e32 v255, v201, v255
	s_add_i32 s46, s12, 3
	v_add_f32_e32 v255, v202, v255
	s_cmpk_lt_u32 s12, 0x7d
	v_add_f32_e32 v255, v203, v255
	s_cselect_b64 s[42:43], -1, 0
	v_add_f32_e32 v255, v204, v255
	s_and_b64 s[44:45], s[42:43], exec
	s_cselect_b32 s44, 0, 0xffffff80
	s_waitcnt lgkmcnt(12)
	v_mfma_f32_32x32x16_bf16 v[66:81], v[102:105], v[122:125], v[66:81]
	v_add_f32_e32 v255, v205, v255
	s_add_i32 s58, s46, s44
	v_add_f32_e32 v255, v206, v255
	s_and_b64 s[42:43], s[42:43], exec
	v_add_f32_e32 v255, v207, v255
	s_cselect_b32 s43, s9, s30
	v_add_f32_e32 v255, v210, v255
	s_cselect_b32 s42, s8, s26
	v_add_f32_e32 v255, v211, v255
	s_lshl_b64 s[44:45], s[58:59], 17
	s_waitcnt lgkmcnt(11)
	v_mfma_f32_32x32x16_bf16 v[82:97], v[106:109], v[118:121], v[82:97]
	v_add_f32_e32 v255, v212, v255
	s_lshl_b64 s[42:43], s[42:43], 11
	v_add_f32_e32 v255, v213, v255
	s_add_u32 s44, s44, s42
	v_add_f32_e32 v255, v214, v255
	s_addc_u32 s45, s45, s43
	v_add_f32_e32 v255, v215, v255
	s_add_u32 s42, s20, s44
	s_addc_u32 s43, s21, s45
	s_waitcnt lgkmcnt(10)
	v_mfma_f32_32x32x16_bf16 v[66:81], v[110:113], v[118:121], v[66:81]
	v_add_f32_e32 v255, v149, v255
	s_add_u32 s44, s22, s44
	v_add_f32_e32 v255, v150, v255
	s_mul_i32 s47, s46, 0xab
	v_add_f32_e32 v255, v151, v255
	s_addc_u32 s45, s23, s45
	v_add_f32_e32 v255, v186, v255
	s_bfe_u32 s47, s47, 0x70009
	v_add_f32_e32 v255, v187, v255
	s_mul_i32 s47, s47, 3
	s_waitcnt lgkmcnt(9)
	v_mfma_f32_32x32x16_bf16 v[82:97], v[134:137], v[114:117], v[82:97]
	v_add_f32_e32 v255, v188, v255
	s_sub_i32 s46, s46, s47
	v_add_f32_e32 v255, v189, v255
	s_and_b32 s46, s46, 0xff
	v_add_f32_e32 v255, v208, v255
	s_lshl_b32 s46, s46, 14
	s_mov_b32 s101, s46
	v_add_f32_e32 v255, v209, v255
	s_add_i32 s46, s46, s27
	v_add_f32_e32 v99, v148, v255
	s_and_b32 s47, s36, 0xc000
	s_add_i32 s47, s47, s31
	s_cmpk_gt_u32 s12, 0x80
	s_cselect_b64 s[10:11], -1, 0
	s_and_b64 vcc, exec, s[10:11]
	s_cbranch_vccnz .LBB0_776
	s_mov_b32 m0, s46
	s_nop 0
	global_load_lds_dwordx4 v146, s[42:43]
	s_mov_b32 m0, s47
	s_nop 0
	global_load_lds_dwordx4 v142, s[44:45]
	s_add_i32 m0, s46, 0x2000
	s_nop 0
	global_load_lds_dwordx4 v144, s[42:43]
	s_add_i32 m0, s47, 0x2000
	s_nop 0
	global_load_lds_dwordx4 v154, s[44:45]
